# grid-barrier spin back-off: s_sleep 1 -> s_sleep 0 in the 55 poll loops
# speedup vs baseline: 1.0026x; 1.0026x over previous
.LBB0_165:
	s_sleep 0
	global_load_dword v2, v0, s[8:9] offset:32 sc1
	s_waitcnt vmcnt(0)
	v_and_b32_e32 v2, 0xffff0000, v2
	v_cmp_ne_u32_e32 vcc, v2, v1
	s_or_b64 s[10:11], vcc, s[10:11]
	s_andn2_b64 exec, exec, s[10:11]
	s_cbranch_execnz .LBB0_165

; __device__ __forceinline__ unsigned xb_ld(unsigned* p)              { return __hip_atomic_load(p, __ATOMIC_RELAXED, __HIP_MEMORY_SCOPE_AGENT); }
; __device__ __forceinline__ void xcd_barrier_complete(unsigned* bar, unsigned x, unsigned& nloc, unsigned& nx) {
;     ...
;     for (;;) {
;         sum = 0u; cnt = 0u; mine = 0u;
; #pragma unroll
;         for (unsigned j = 0; j < 16; ++j) { const unsigned c = xb_ld(&bar[XB_XCNT(j)]); sum += c; cnt += (c > 0u) ? 1u : 0u; mine = (j == x) ? c : mine; }
;         if (sum == G) break;
;         __builtin_amdgcn_s_sleep(1);
;         if ((++sp & 255u) == 0u) { if (xb_ld(&bar[XB_TMO])) break; if (sp > XB_SPIN_CAP) { atomicAdd(&bar[XB_TMO], 1u); break; } }
;     }
.LBB0_174:
	global_load_dword v15, v16, s[14:15] sc1
	s_waitcnt lgkmcnt(0)
	global_load_dword v0, v16, s[16:17] sc1
	global_load_dword v1, v16, s[18:19] sc1
	global_load_dword v2, v16, s[20:21] sc1
	global_load_dword v3, v16, s[22:23] sc1
	global_load_dword v4, v16, s[24:25] sc1
	global_load_dword v5, v16, s[26:27] sc1
	global_load_dword v6, v16, s[30:31] sc1
	global_load_dword v7, v16, s[34:35] sc1
	global_load_dword v8, v16, s[36:37] sc1
	global_load_dword v9, v16, s[38:39] sc1
	global_load_dword v10, v16, s[40:41] sc1
	global_load_dword v11, v16, s[42:43] sc1
	global_load_dword v12, v16, s[44:45] sc1
	global_load_dword v13, v16, s[46:47] sc1
	global_load_dword v14, v16, s[48:49] sc1
	s_mov_b64 s[50:51], -1
	s_mov_b64 s[52:53], -1
	s_waitcnt vmcnt(14)
	v_add_u32_e32 v17, v0, v15
	s_waitcnt vmcnt(13)
	v_add_u32_e32 v17, v17, v1
	s_waitcnt vmcnt(12)
	v_add_u32_e32 v17, v17, v2
	s_waitcnt vmcnt(11)
	v_add_u32_e32 v17, v17, v3
	s_waitcnt vmcnt(10)
	v_add_u32_e32 v17, v17, v4
	s_waitcnt vmcnt(9)
	v_add_u32_e32 v17, v17, v5
	s_waitcnt vmcnt(8)
	v_add_u32_e32 v17, v17, v6
	s_waitcnt vmcnt(7)
	v_add_u32_e32 v17, v17, v7
	s_waitcnt vmcnt(6)
	v_add_u32_e32 v17, v17, v8
	s_waitcnt vmcnt(5)
	v_add_u32_e32 v17, v17, v9
	s_waitcnt vmcnt(4)
	v_add_u32_e32 v17, v17, v10
	s_waitcnt vmcnt(3)
	v_add_u32_e32 v17, v17, v11
	s_waitcnt vmcnt(2)
	v_add_u32_e32 v17, v17, v12
	s_waitcnt vmcnt(1)
	v_add_u32_e32 v17, v17, v13
	s_waitcnt vmcnt(0)
	v_add_u32_e32 v17, v17, v14
	v_cmp_eq_u32_e32 vcc, s4, v17
	s_cbranch_vccnz .LBB0_173
	s_and_b32 s12, s5, 0xff
	s_cmp_eq_u32 s12, 0
	s_mov_b64 s[54:55], -1
	s_sleep 0
	s_cbranch_scc1 .LBB0_178
	s_and_b64 vcc, exec, s[54:55]
	s_cbranch_vccz .LBB0_173

; __device__ __forceinline__ unsigned xb_ld(unsigned* p)              { return __hip_atomic_load(p, __ATOMIC_RELAXED, __HIP_MEMORY_SCOPE_AGENT); }
; __device__ __forceinline__ unsigned xb_add(unsigned* p, unsigned v) { return __hip_atomic_fetch_add(p, v, __ATOMIC_RELAXED, __HIP_MEMORY_SCOPE_AGENT); }
; #define XB_SPIN(cond, bar) do { unsigned _sp = 0; while (cond) { __builtin_amdgcn_s_sleep(1); \
;     if ((++_sp & 255u) == 0u) { if (xb_ld(&(bar)[XB_TMO])) break; if (_sp > XB_SPIN_CAP) { atomicAdd(&(bar)[XB_TMO], 1u); break; } } } } while (0)
; __device__ __forceinline__ void xcd_barrier(const XcdBarrier& b) {
;     ...
;             else XB_SPIN(xb_ld(&bar[XB_TOPGEN]) == tg, bar);
;             __builtin_amdgcn_fence(__ATOMIC_ACQUIRE, "agent");
;             xb_add(&bar[XB_XGEN(b.x)], 1u);
;             asm volatile("s_waitcnt vmcnt(0)" ::: "memory");
;         } else {
;             XB_SPIN(xb_ld(&bar[XB_XGEN(b.x)]) == gen, bar);
.LBB0_192:
	s_and_b32 s4, s3, 0xff
	s_mov_b64 s[26:27], -1
	s_cmp_lg_u32 s4, 0
	s_mov_b64 s[34:35], -1
	s_sleep 0
	s_cbranch_scc0 .LBB0_195
	s_and_b64 vcc, exec, s[34:35]
	s_cbranch_vccz .LBB0_191

; __device__ __forceinline__ unsigned xb_ld(unsigned* p)              { return __hip_atomic_load(p, __ATOMIC_RELAXED, __HIP_MEMORY_SCOPE_AGENT); }
; __device__ __forceinline__ unsigned xb_add(unsigned* p, unsigned v) { return __hip_atomic_fetch_add(p, v, __ATOMIC_RELAXED, __HIP_MEMORY_SCOPE_AGENT); }
; #define XB_SPIN(cond, bar) do { unsigned _sp = 0; while (cond) { __builtin_amdgcn_s_sleep(1); \
;     if ((++_sp & 255u) == 0u) { if (xb_ld(&(bar)[XB_TMO])) break; if (_sp > XB_SPIN_CAP) { atomicAdd(&(bar)[XB_TMO], 1u); break; } } } } while (0)
; __device__ __forceinline__ void xcd_barrier(const XcdBarrier& b) {
;     ...
;             else XB_SPIN(xb_ld(&bar[XB_TOPGEN]) == tg, bar);
;             __builtin_amdgcn_fence(__ATOMIC_ACQUIRE, "agent");
;             xb_add(&bar[XB_XGEN(b.x)], 1u);
;             asm volatile("s_waitcnt vmcnt(0)" ::: "memory");
;         } else {
;             XB_SPIN(xb_ld(&bar[XB_XGEN(b.x)]) == gen, bar);
.LBB0_209:
	s_and_b32 s4, s3, 0xff
	s_cmp_lg_u32 s4, 0
	s_mov_b64 s[26:27], -1
	s_sleep 0
	s_cbranch_scc0 .LBB0_212
	s_mov_b64 s[30:31], -1
	s_and_b64 vcc, exec, s[26:27]
	s_cbranch_vccz .LBB0_208

; __device__ __forceinline__ unsigned xb_ld(unsigned* p)              { return __hip_atomic_load(p, __ATOMIC_RELAXED, __HIP_MEMORY_SCOPE_AGENT); }
; __device__ __forceinline__ void xcd_barrier_complete(unsigned* bar, unsigned x, unsigned& nloc, unsigned& nx) {
;     ...
;     for (;;) {
;         sum = 0u; cnt = 0u; mine = 0u;
; #pragma unroll
;         for (unsigned j = 0; j < 16; ++j) { const unsigned c = xb_ld(&bar[XB_XCNT(j)]); sum += c; cnt += (c > 0u) ? 1u : 0u; mine = (j == x) ? c : mine; }
;         if (sum == G) break;
;         __builtin_amdgcn_s_sleep(1);
;         if ((++sp & 255u) == 0u) { if (xb_ld(&bar[XB_TMO])) break; if (sp > XB_SPIN_CAP) { atomicAdd(&bar[XB_TMO], 1u); break; } }
;     }
.LBB0_239:
	global_load_dword v15, v16, s[14:15] sc1
	s_waitcnt lgkmcnt(0)
	global_load_dword v0, v16, s[16:17] sc1
	global_load_dword v1, v16, s[18:19] sc1
	global_load_dword v2, v16, s[20:21] sc1
	global_load_dword v3, v16, s[22:23] sc1
	global_load_dword v4, v16, s[24:25] sc1
	global_load_dword v5, v16, s[26:27] sc1
	global_load_dword v6, v16, s[38:39] sc1
	global_load_dword v7, v16, s[40:41] sc1
	global_load_dword v8, v16, s[42:43] sc1
	global_load_dword v9, v16, s[44:45] sc1
	global_load_dword v10, v16, s[46:47] sc1
	global_load_dword v11, v16, s[48:49] sc1
	global_load_dword v12, v16, s[50:51] sc1
	global_load_dword v13, v16, s[52:53] sc1
	global_load_dword v14, v16, s[54:55] sc1
	s_mov_b64 s[56:57], -1
	s_mov_b64 s[58:59], -1
	s_waitcnt vmcnt(14)
	v_add_u32_e32 v17, v0, v15
	s_waitcnt vmcnt(13)
	v_add_u32_e32 v17, v17, v1
	s_waitcnt vmcnt(12)
	v_add_u32_e32 v17, v17, v2
	s_waitcnt vmcnt(11)
	v_add_u32_e32 v17, v17, v3
	s_waitcnt vmcnt(10)
	v_add_u32_e32 v17, v17, v4
	s_waitcnt vmcnt(9)
	v_add_u32_e32 v17, v17, v5
	s_waitcnt vmcnt(8)
	v_add_u32_e32 v17, v17, v6
	s_waitcnt vmcnt(7)
	v_add_u32_e32 v17, v17, v7
	s_waitcnt vmcnt(6)
	v_add_u32_e32 v17, v17, v8
	s_waitcnt vmcnt(5)
	v_add_u32_e32 v17, v17, v9
	s_waitcnt vmcnt(4)
	v_add_u32_e32 v17, v17, v10
	s_waitcnt vmcnt(3)
	v_add_u32_e32 v17, v17, v11
	s_waitcnt vmcnt(2)
	v_add_u32_e32 v17, v17, v12
	s_waitcnt vmcnt(1)
	v_add_u32_e32 v17, v17, v13
	s_waitcnt vmcnt(0)
	v_add_u32_e32 v17, v17, v14
	v_cmp_eq_u32_e32 vcc, s4, v17
	s_cbranch_vccnz .LBB0_238
	s_and_b32 s12, s5, 0xff
	s_cmp_eq_u32 s12, 0
	s_mov_b64 s[60:61], -1
	s_sleep 0
	s_cbranch_scc1 .LBB0_243
	s_and_b64 vcc, exec, s[60:61]
	s_cbranch_vccz .LBB0_238

; __device__ __forceinline__ unsigned xb_ld(unsigned* p)              { return __hip_atomic_load(p, __ATOMIC_RELAXED, __HIP_MEMORY_SCOPE_AGENT); }
; __device__ __forceinline__ unsigned xb_add(unsigned* p, unsigned v) { return __hip_atomic_fetch_add(p, v, __ATOMIC_RELAXED, __HIP_MEMORY_SCOPE_AGENT); }
; #define XB_SPIN(cond, bar) do { unsigned _sp = 0; while (cond) { __builtin_amdgcn_s_sleep(1); \
;     if ((++_sp & 255u) == 0u) { if (xb_ld(&(bar)[XB_TMO])) break; if (_sp > XB_SPIN_CAP) { atomicAdd(&(bar)[XB_TMO], 1u); break; } } } } while (0)
; __device__ __forceinline__ void xcd_barrier(const XcdBarrier& b) {
;     ...
;             else XB_SPIN(xb_ld(&bar[XB_TOPGEN]) == tg, bar);
;             __builtin_amdgcn_fence(__ATOMIC_ACQUIRE, "agent");
;             xb_add(&bar[XB_XGEN(b.x)], 1u);
;             asm volatile("s_waitcnt vmcnt(0)" ::: "memory");
;         } else {
;             XB_SPIN(xb_ld(&bar[XB_XGEN(b.x)]) == gen, bar);
.LBB0_257:
	s_and_b32 s4, s3, 0xff
	s_mov_b64 s[26:27], -1
	s_cmp_lg_u32 s4, 0
	s_mov_b64 s[40:41], -1
	s_sleep 0
	s_cbranch_scc0 .LBB0_260
	s_and_b64 vcc, exec, s[40:41]
	s_cbranch_vccz .LBB0_256

; __device__ __forceinline__ unsigned xb_ld(unsigned* p)              { return __hip_atomic_load(p, __ATOMIC_RELAXED, __HIP_MEMORY_SCOPE_AGENT); }
; __device__ __forceinline__ unsigned xb_add(unsigned* p, unsigned v) { return __hip_atomic_fetch_add(p, v, __ATOMIC_RELAXED, __HIP_MEMORY_SCOPE_AGENT); }
; #define XB_SPIN(cond, bar) do { unsigned _sp = 0; while (cond) { __builtin_amdgcn_s_sleep(1); \
;     if ((++_sp & 255u) == 0u) { if (xb_ld(&(bar)[XB_TMO])) break; if (_sp > XB_SPIN_CAP) { atomicAdd(&(bar)[XB_TMO], 1u); break; } } } } while (0)
; __device__ __forceinline__ void xcd_barrier(const XcdBarrier& b) {
;     ...
;             else XB_SPIN(xb_ld(&bar[XB_TOPGEN]) == tg, bar);
;             __builtin_amdgcn_fence(__ATOMIC_ACQUIRE, "agent");
;             xb_add(&bar[XB_XGEN(b.x)], 1u);
;             asm volatile("s_waitcnt vmcnt(0)" ::: "memory");
;         } else {
;             XB_SPIN(xb_ld(&bar[XB_XGEN(b.x)]) == gen, bar);
.LBB0_274:
	s_and_b32 s4, s3, 0xff
	s_cmp_lg_u32 s4, 0
	s_mov_b64 s[26:27], -1
	s_sleep 0
	s_cbranch_scc0 .LBB0_277
	s_mov_b64 s[38:39], -1
	s_and_b64 vcc, exec, s[26:27]
	s_cbranch_vccz .LBB0_273

; __device__ __forceinline__ unsigned xb_ld(unsigned* p)              { return __hip_atomic_load(p, __ATOMIC_RELAXED, __HIP_MEMORY_SCOPE_AGENT); }
; __device__ __forceinline__ void xcd_barrier_complete(unsigned* bar, unsigned x, unsigned& nloc, unsigned& nx) {
;     ...
;     for (;;) {
;         sum = 0u; cnt = 0u; mine = 0u;
; #pragma unroll
;         for (unsigned j = 0; j < 16; ++j) { const unsigned c = xb_ld(&bar[XB_XCNT(j)]); sum += c; cnt += (c > 0u) ? 1u : 0u; mine = (j == x) ? c : mine; }
;         if (sum == G) break;
;         __builtin_amdgcn_s_sleep(1);
;         if ((++sp & 255u) == 0u) { if (xb_ld(&bar[XB_TMO])) break; if (sp > XB_SPIN_CAP) { atomicAdd(&bar[XB_TMO], 1u); break; } }
;     }
.LBB0_426:
	global_load_dword v15, v16, s[16:17] sc1
	s_waitcnt lgkmcnt(0)
	global_load_dword v0, v16, s[18:19] sc1
	global_load_dword v1, v16, s[20:21] sc1
	global_load_dword v2, v16, s[22:23] sc1
	global_load_dword v3, v16, s[24:25] sc1
	global_load_dword v4, v16, s[26:27] sc1
	global_load_dword v5, v16, s[38:39] sc1
	global_load_dword v6, v16, s[40:41] sc1
	global_load_dword v7, v16, s[42:43] sc1
	global_load_dword v8, v16, s[44:45] sc1
	global_load_dword v9, v16, s[46:47] sc1
	global_load_dword v10, v16, s[48:49] sc1
	global_load_dword v11, v16, s[50:51] sc1
	global_load_dword v12, v16, s[52:53] sc1
	global_load_dword v13, v16, s[54:55] sc1
	global_load_dword v14, v16, s[56:57] sc1
	s_mov_b64 s[58:59], -1
	s_mov_b64 s[60:61], -1
	s_waitcnt vmcnt(14)
	v_add_u32_e32 v17, v0, v15
	s_waitcnt vmcnt(13)
	v_add_u32_e32 v17, v17, v1
	s_waitcnt vmcnt(12)
	v_add_u32_e32 v17, v17, v2
	s_waitcnt vmcnt(11)
	v_add_u32_e32 v17, v17, v3
	s_waitcnt vmcnt(10)
	v_add_u32_e32 v17, v17, v4
	s_waitcnt vmcnt(9)
	v_add_u32_e32 v17, v17, v5
	s_waitcnt vmcnt(8)
	v_add_u32_e32 v17, v17, v6
	s_waitcnt vmcnt(7)
	v_add_u32_e32 v17, v17, v7
	s_waitcnt vmcnt(6)
	v_add_u32_e32 v17, v17, v8
	s_waitcnt vmcnt(5)
	v_add_u32_e32 v17, v17, v9
	s_waitcnt vmcnt(4)
	v_add_u32_e32 v17, v17, v10
	s_waitcnt vmcnt(3)
	v_add_u32_e32 v17, v17, v11
	s_waitcnt vmcnt(2)
	v_add_u32_e32 v17, v17, v12
	s_waitcnt vmcnt(1)
	v_add_u32_e32 v17, v17, v13
	s_waitcnt vmcnt(0)
	v_add_u32_e32 v17, v17, v14
	v_cmp_eq_u32_e32 vcc, s4, v17
	s_cbranch_vccnz .LBB0_425
	s_and_b32 s12, s5, 0xff
	s_cmp_eq_u32 s12, 0
	s_mov_b64 s[62:63], -1
	s_sleep 0
	s_cbranch_scc1 .LBB0_430
	s_and_b64 vcc, exec, s[62:63]
	s_cbranch_vccz .LBB0_425

; __device__ __forceinline__ unsigned xb_ld(unsigned* p)              { return __hip_atomic_load(p, __ATOMIC_RELAXED, __HIP_MEMORY_SCOPE_AGENT); }
; __device__ __forceinline__ unsigned xb_add(unsigned* p, unsigned v) { return __hip_atomic_fetch_add(p, v, __ATOMIC_RELAXED, __HIP_MEMORY_SCOPE_AGENT); }
; #define XB_SPIN(cond, bar) do { unsigned _sp = 0; while (cond) { __builtin_amdgcn_s_sleep(1); \
;     if ((++_sp & 255u) == 0u) { if (xb_ld(&(bar)[XB_TMO])) break; if (_sp > XB_SPIN_CAP) { atomicAdd(&(bar)[XB_TMO], 1u); break; } } } } while (0)
; __device__ __forceinline__ void xcd_barrier(const XcdBarrier& b) {
;     ...
;             else XB_SPIN(xb_ld(&bar[XB_TOPGEN]) == tg, bar);
;             __builtin_amdgcn_fence(__ATOMIC_ACQUIRE, "agent");
;             xb_add(&bar[XB_XGEN(b.x)], 1u);
;             asm volatile("s_waitcnt vmcnt(0)" ::: "memory");
;         } else {
;             XB_SPIN(xb_ld(&bar[XB_XGEN(b.x)]) == gen, bar);
.LBB0_444:
	s_and_b32 s4, s3, 0xff
	s_mov_b64 s[38:39], -1
	s_cmp_lg_u32 s4, 0
	s_mov_b64 s[42:43], -1
	s_sleep 0
	s_cbranch_scc0 .LBB0_447
	s_and_b64 vcc, exec, s[42:43]
	s_cbranch_vccz .LBB0_443

; __device__ __forceinline__ unsigned xb_ld(unsigned* p)              { return __hip_atomic_load(p, __ATOMIC_RELAXED, __HIP_MEMORY_SCOPE_AGENT); }
; __device__ __forceinline__ unsigned xb_add(unsigned* p, unsigned v) { return __hip_atomic_fetch_add(p, v, __ATOMIC_RELAXED, __HIP_MEMORY_SCOPE_AGENT); }
; #define XB_SPIN(cond, bar) do { unsigned _sp = 0; while (cond) { __builtin_amdgcn_s_sleep(1); \
;     if ((++_sp & 255u) == 0u) { if (xb_ld(&(bar)[XB_TMO])) break; if (_sp > XB_SPIN_CAP) { atomicAdd(&(bar)[XB_TMO], 1u); break; } } } } while (0)
; __device__ __forceinline__ void xcd_barrier(const XcdBarrier& b) {
;     ...
;             else XB_SPIN(xb_ld(&bar[XB_TOPGEN]) == tg, bar);
;             __builtin_amdgcn_fence(__ATOMIC_ACQUIRE, "agent");
;             xb_add(&bar[XB_XGEN(b.x)], 1u);
;             asm volatile("s_waitcnt vmcnt(0)" ::: "memory");
;         } else {
;             XB_SPIN(xb_ld(&bar[XB_XGEN(b.x)]) == gen, bar);
.LBB0_461:
	s_and_b32 s4, s3, 0xff
	s_cmp_lg_u32 s4, 0
	s_mov_b64 s[38:39], -1
	s_sleep 0
	s_cbranch_scc0 .LBB0_464
	s_mov_b64 s[40:41], -1
	s_and_b64 vcc, exec, s[38:39]
	s_cbranch_vccz .LBB0_460

; __device__ __forceinline__ unsigned xb_ld(unsigned* p)              { return __hip_atomic_load(p, __ATOMIC_RELAXED, __HIP_MEMORY_SCOPE_AGENT); }
; __device__ __forceinline__ void xcd_barrier_complete(unsigned* bar, unsigned x, unsigned& nloc, unsigned& nx) {
;     ...
;     for (;;) {
;         sum = 0u; cnt = 0u; mine = 0u;
; #pragma unroll
;         for (unsigned j = 0; j < 16; ++j) { const unsigned c = xb_ld(&bar[XB_XCNT(j)]); sum += c; cnt += (c > 0u) ? 1u : 0u; mine = (j == x) ? c : mine; }
;         if (sum == G) break;
;         __builtin_amdgcn_s_sleep(1);
;         if ((++sp & 255u) == 0u) { if (xb_ld(&bar[XB_TMO])) break; if (sp > XB_SPIN_CAP) { atomicAdd(&bar[XB_TMO], 1u); break; } }
;     }
.LBB0_495:
	global_load_dword v15, v129, s[16:17] sc1
	s_waitcnt lgkmcnt(0)
	global_load_dword v0, v129, s[22:23] sc1
	global_load_dword v1, v129, s[26:27] sc1
	global_load_dword v2, v129, s[38:39] sc1
	global_load_dword v3, v129, s[40:41] sc1
	global_load_dword v4, v129, s[54:55] sc1
	global_load_dword v5, v129, s[56:57] sc1
	global_load_dword v6, v129, s[58:59] sc1
	global_load_dword v7, v129, s[62:63] sc1
	global_load_dword v8, v129, s[74:75] sc1
	global_load_dword v9, v129, s[76:77] sc1
	global_load_dword v10, v129, s[78:79] sc1
	global_load_dword v11, v129, s[80:81] sc1
	global_load_dword v12, v129, s[82:83] sc1
	global_load_dword v13, v129, s[84:85] sc1
	global_load_dword v14, v129, s[86:87] sc1
	s_mov_b64 s[88:89], -1
	s_mov_b64 s[90:91], -1
	s_waitcnt vmcnt(14)
	v_add_u32_e32 v16, v0, v15
	s_waitcnt vmcnt(13)
	v_add_u32_e32 v16, v16, v1
	s_waitcnt vmcnt(12)
	v_add_u32_e32 v16, v16, v2
	s_waitcnt vmcnt(11)
	v_add_u32_e32 v16, v16, v3
	s_waitcnt vmcnt(10)
	v_add_u32_e32 v16, v16, v4
	s_waitcnt vmcnt(9)
	v_add_u32_e32 v16, v16, v5
	s_waitcnt vmcnt(8)
	v_add_u32_e32 v16, v16, v6
	s_waitcnt vmcnt(7)
	v_add_u32_e32 v16, v16, v7
	s_waitcnt vmcnt(6)
	v_add_u32_e32 v16, v16, v8
	s_waitcnt vmcnt(5)
	v_add_u32_e32 v16, v16, v9
	s_waitcnt vmcnt(4)
	v_add_u32_e32 v16, v16, v10
	s_waitcnt vmcnt(3)
	v_add_u32_e32 v16, v16, v11
	s_waitcnt vmcnt(2)
	v_add_u32_e32 v16, v16, v12
	s_waitcnt vmcnt(1)
	v_add_u32_e32 v16, v16, v13
	s_waitcnt vmcnt(0)
	v_add_u32_e32 v16, v16, v14
	v_cmp_eq_u32_e32 vcc, s0, v16
	s_cbranch_vccnz .LBB0_494
	s_and_b32 s12, s5, 0xff
	s_cmp_eq_u32 s12, 0
	s_mov_b64 s[92:93], -1
	s_sleep 0
	s_cbranch_scc1 .LBB0_499
	s_and_b64 vcc, exec, s[92:93]
	s_cbranch_vccz .LBB0_494

; __device__ __forceinline__ unsigned xb_ld(unsigned* p)              { return __hip_atomic_load(p, __ATOMIC_RELAXED, __HIP_MEMORY_SCOPE_AGENT); }
; __device__ __forceinline__ unsigned xb_add(unsigned* p, unsigned v) { return __hip_atomic_fetch_add(p, v, __ATOMIC_RELAXED, __HIP_MEMORY_SCOPE_AGENT); }
; #define XB_SPIN(cond, bar) do { unsigned _sp = 0; while (cond) { __builtin_amdgcn_s_sleep(1); \
;     if ((++_sp & 255u) == 0u) { if (xb_ld(&(bar)[XB_TMO])) break; if (_sp > XB_SPIN_CAP) { atomicAdd(&(bar)[XB_TMO], 1u); break; } } } } while (0)
; __device__ __forceinline__ void xcd_barrier(const XcdBarrier& b) {
;     ...
;             else XB_SPIN(xb_ld(&bar[XB_TOPGEN]) == tg, bar);
;             __builtin_amdgcn_fence(__ATOMIC_ACQUIRE, "agent");
;             xb_add(&bar[XB_XGEN(b.x)], 1u);
;             asm volatile("s_waitcnt vmcnt(0)" ::: "memory");
;         } else {
;             XB_SPIN(xb_ld(&bar[XB_XGEN(b.x)]) == gen, bar);
.LBB0_513:
	s_and_b32 s5, s4, 0xff
	s_mov_b64 s[56:57], -1
	s_cmp_lg_u32 s5, 0
	s_mov_b64 s[62:63], -1
	s_sleep 0
	s_cbranch_scc0 .LBB0_516
	s_and_b64 vcc, exec, s[62:63]
	s_cbranch_vccz .LBB0_512

; __device__ __forceinline__ unsigned xb_ld(unsigned* p)              { return __hip_atomic_load(p, __ATOMIC_RELAXED, __HIP_MEMORY_SCOPE_AGENT); }
; __device__ __forceinline__ unsigned xb_add(unsigned* p, unsigned v) { return __hip_atomic_fetch_add(p, v, __ATOMIC_RELAXED, __HIP_MEMORY_SCOPE_AGENT); }
; #define XB_SPIN(cond, bar) do { unsigned _sp = 0; while (cond) { __builtin_amdgcn_s_sleep(1); \
;     if ((++_sp & 255u) == 0u) { if (xb_ld(&(bar)[XB_TMO])) break; if (_sp > XB_SPIN_CAP) { atomicAdd(&(bar)[XB_TMO], 1u); break; } } } } while (0)
; __device__ __forceinline__ void xcd_barrier(const XcdBarrier& b) {
;     ...
;             else XB_SPIN(xb_ld(&bar[XB_TOPGEN]) == tg, bar);
;             __builtin_amdgcn_fence(__ATOMIC_ACQUIRE, "agent");
;             xb_add(&bar[XB_XGEN(b.x)], 1u);
;             asm volatile("s_waitcnt vmcnt(0)" ::: "memory");
;         } else {
;             XB_SPIN(xb_ld(&bar[XB_XGEN(b.x)]) == gen, bar);
.LBB0_530:
	s_and_b32 s5, s4, 0xff
	s_mov_b64 s[54:55], -1
	s_cmp_lg_u32 s5, 0
	s_mov_b64 s[58:59], -1
	s_sleep 0
	s_cbranch_scc0 .LBB0_533
	s_and_b64 vcc, exec, s[58:59]
	s_cbranch_vccz .LBB0_529

; __device__ __forceinline__ unsigned xb_ld(unsigned* p)              { return __hip_atomic_load(p, __ATOMIC_RELAXED, __HIP_MEMORY_SCOPE_AGENT); }
; __device__ __forceinline__ void xcd_barrier_complete(unsigned* bar, unsigned x, unsigned& nloc, unsigned& nx) {
;     ...
;     for (;;) {
;         sum = 0u; cnt = 0u; mine = 0u;
; #pragma unroll
;         for (unsigned j = 0; j < 16; ++j) { const unsigned c = xb_ld(&bar[XB_XCNT(j)]); sum += c; cnt += (c > 0u) ? 1u : 0u; mine = (j == x) ? c : mine; }
;         if (sum == G) break;
;         __builtin_amdgcn_s_sleep(1);
;         if ((++sp & 255u) == 0u) { if (xb_ld(&bar[XB_TMO])) break; if (sp > XB_SPIN_CAP) { atomicAdd(&bar[XB_TMO], 1u); break; } }
;     }
.LBB0_603:
	global_load_dword v15, v129, s[22:23] sc1
	s_waitcnt lgkmcnt(0)
	global_load_dword v0, v129, s[38:39] sc1
	global_load_dword v1, v129, s[40:41] sc1
	global_load_dword v2, v129, s[54:55] sc1
	global_load_dword v3, v129, s[56:57] sc1
	global_load_dword v4, v129, s[58:59] sc1
	global_load_dword v5, v129, s[62:63] sc1
	global_load_dword v6, v129, s[72:73] sc1
	global_load_dword v7, v129, s[74:75] sc1
	global_load_dword v8, v129, s[76:77] sc1
	global_load_dword v9, v129, s[78:79] sc1
	global_load_dword v10, v129, s[80:81] sc1
	global_load_dword v11, v129, s[82:83] sc1
	global_load_dword v12, v129, s[84:85] sc1
	global_load_dword v13, v129, s[86:87] sc1
	global_load_dword v14, v129, s[88:89] sc1
	s_mov_b64 s[90:91], -1
	s_mov_b64 s[92:93], -1
	s_waitcnt vmcnt(14)
	v_add_u32_e32 v16, v0, v15
	s_waitcnt vmcnt(13)
	v_add_u32_e32 v16, v16, v1
	s_waitcnt vmcnt(12)
	v_add_u32_e32 v16, v16, v2
	s_waitcnt vmcnt(11)
	v_add_u32_e32 v16, v16, v3
	s_waitcnt vmcnt(10)
	v_add_u32_e32 v16, v16, v4
	s_waitcnt vmcnt(9)
	v_add_u32_e32 v16, v16, v5
	s_waitcnt vmcnt(8)
	v_add_u32_e32 v16, v16, v6
	s_waitcnt vmcnt(7)
	v_add_u32_e32 v16, v16, v7
	s_waitcnt vmcnt(6)
	v_add_u32_e32 v16, v16, v8
	s_waitcnt vmcnt(5)
	v_add_u32_e32 v16, v16, v9
	s_waitcnt vmcnt(4)
	v_add_u32_e32 v16, v16, v10
	s_waitcnt vmcnt(3)
	v_add_u32_e32 v16, v16, v11
	s_waitcnt vmcnt(2)
	v_add_u32_e32 v16, v16, v12
	s_waitcnt vmcnt(1)
	v_add_u32_e32 v16, v16, v13
	s_waitcnt vmcnt(0)
	v_add_u32_e32 v16, v16, v14
	v_cmp_eq_u32_e32 vcc, s0, v16
	s_cbranch_vccnz .LBB0_602
	s_and_b32 s12, s5, 0xff
	s_cmp_eq_u32 s12, 0
	s_mov_b64 s[94:95], -1
	s_sleep 0
	s_cbranch_scc1 .LBB0_607
	s_and_b64 vcc, exec, s[94:95]
	s_cbranch_vccz .LBB0_602

; __device__ __forceinline__ unsigned xb_ld(unsigned* p)              { return __hip_atomic_load(p, __ATOMIC_RELAXED, __HIP_MEMORY_SCOPE_AGENT); }
; __device__ __forceinline__ unsigned xb_add(unsigned* p, unsigned v) { return __hip_atomic_fetch_add(p, v, __ATOMIC_RELAXED, __HIP_MEMORY_SCOPE_AGENT); }
; #define XB_SPIN(cond, bar) do { unsigned _sp = 0; while (cond) { __builtin_amdgcn_s_sleep(1); \
;     if ((++_sp & 255u) == 0u) { if (xb_ld(&(bar)[XB_TMO])) break; if (_sp > XB_SPIN_CAP) { atomicAdd(&(bar)[XB_TMO], 1u); break; } } } } while (0)
; __device__ __forceinline__ void xcd_barrier(const XcdBarrier& b) {
;     ...
;             else XB_SPIN(xb_ld(&bar[XB_TOPGEN]) == tg, bar);
;             __builtin_amdgcn_fence(__ATOMIC_ACQUIRE, "agent");
;             xb_add(&bar[XB_XGEN(b.x)], 1u);
;             asm volatile("s_waitcnt vmcnt(0)" ::: "memory");
;         } else {
;             XB_SPIN(xb_ld(&bar[XB_XGEN(b.x)]) == gen, bar);
.LBB0_621:
	s_and_b32 s5, s4, 0xff
	s_mov_b64 s[62:63], -1
	s_cmp_lg_u32 s5, 0
	s_mov_b64 s[74:75], -1
	s_sleep 0
	s_cbranch_scc0 .LBB0_624
	s_and_b64 vcc, exec, s[74:75]
	s_cbranch_vccz .LBB0_620

; __device__ __forceinline__ unsigned xb_ld(unsigned* p)              { return __hip_atomic_load(p, __ATOMIC_RELAXED, __HIP_MEMORY_SCOPE_AGENT); }
; __device__ __forceinline__ unsigned xb_add(unsigned* p, unsigned v) { return __hip_atomic_fetch_add(p, v, __ATOMIC_RELAXED, __HIP_MEMORY_SCOPE_AGENT); }
; #define XB_SPIN(cond, bar) do { unsigned _sp = 0; while (cond) { __builtin_amdgcn_s_sleep(1); \
;     if ((++_sp & 255u) == 0u) { if (xb_ld(&(bar)[XB_TMO])) break; if (_sp > XB_SPIN_CAP) { atomicAdd(&(bar)[XB_TMO], 1u); break; } } } } while (0)
; __device__ __forceinline__ void xcd_barrier(const XcdBarrier& b) {
;     ...
;             else XB_SPIN(xb_ld(&bar[XB_TOPGEN]) == tg, bar);
;             __builtin_amdgcn_fence(__ATOMIC_ACQUIRE, "agent");
;             xb_add(&bar[XB_XGEN(b.x)], 1u);
;             asm volatile("s_waitcnt vmcnt(0)" ::: "memory");
;         } else {
;             XB_SPIN(xb_ld(&bar[XB_XGEN(b.x)]) == gen, bar);
.LBB0_638:
	s_and_b32 s5, s4, 0xff
	s_mov_b64 s[58:59], -1
	s_cmp_lg_u32 s5, 0
	s_mov_b64 s[72:73], -1
	s_sleep 0
	s_cbranch_scc0 .LBB0_641
	s_and_b64 vcc, exec, s[72:73]
	s_cbranch_vccz .LBB0_637

; __device__ __forceinline__ unsigned xb_ld(unsigned* p)              { return __hip_atomic_load(p, __ATOMIC_RELAXED, __HIP_MEMORY_SCOPE_AGENT); }
; __device__ __forceinline__ void xcd_barrier_complete(unsigned* bar, unsigned x, unsigned& nloc, unsigned& nx) {
;     ...
;     for (;;) {
;         sum = 0u; cnt = 0u; mine = 0u;
; #pragma unroll
;         for (unsigned j = 0; j < 16; ++j) { const unsigned c = xb_ld(&bar[XB_XCNT(j)]); sum += c; cnt += (c > 0u) ? 1u : 0u; mine = (j == x) ? c : mine; }
;         if (sum == G) break;
;         __builtin_amdgcn_s_sleep(1);
;         if ((++sp & 255u) == 0u) { if (xb_ld(&bar[XB_TMO])) break; if (sp > XB_SPIN_CAP) { atomicAdd(&bar[XB_TMO], 1u); break; } }
;     }
.LBB0_691:
	global_load_dword v15, v129, s[22:23] sc1
	s_waitcnt lgkmcnt(0)
	global_load_dword v0, v129, s[26:27] sc1
	global_load_dword v1, v129, s[38:39] sc1
	global_load_dword v2, v129, s[40:41] sc1
	global_load_dword v3, v129, s[54:55] sc1
	global_load_dword v4, v129, s[56:57] sc1
	global_load_dword v5, v129, s[58:59] sc1
	global_load_dword v6, v129, s[62:63] sc1
	global_load_dword v7, v129, s[72:73] sc1
	global_load_dword v8, v129, s[74:75] sc1
	global_load_dword v9, v129, s[76:77] sc1
	global_load_dword v10, v129, s[78:79] sc1
	global_load_dword v11, v129, s[80:81] sc1
	global_load_dword v12, v129, s[82:83] sc1
	global_load_dword v13, v129, s[84:85] sc1
	global_load_dword v14, v129, s[86:87] sc1
	s_mov_b64 s[88:89], -1
	s_mov_b64 s[90:91], -1
	s_waitcnt vmcnt(14)
	v_add_u32_e32 v16, v0, v15
	s_waitcnt vmcnt(13)
	v_add_u32_e32 v16, v16, v1
	s_waitcnt vmcnt(12)
	v_add_u32_e32 v16, v16, v2
	s_waitcnt vmcnt(11)
	v_add_u32_e32 v16, v16, v3
	s_waitcnt vmcnt(10)
	v_add_u32_e32 v16, v16, v4
	s_waitcnt vmcnt(9)
	v_add_u32_e32 v16, v16, v5
	s_waitcnt vmcnt(8)
	v_add_u32_e32 v16, v16, v6
	s_waitcnt vmcnt(7)
	v_add_u32_e32 v16, v16, v7
	s_waitcnt vmcnt(6)
	v_add_u32_e32 v16, v16, v8
	s_waitcnt vmcnt(5)
	v_add_u32_e32 v16, v16, v9
	s_waitcnt vmcnt(4)
	v_add_u32_e32 v16, v16, v10
	s_waitcnt vmcnt(3)
	v_add_u32_e32 v16, v16, v11
	s_waitcnt vmcnt(2)
	v_add_u32_e32 v16, v16, v12
	s_waitcnt vmcnt(1)
	v_add_u32_e32 v16, v16, v13
	s_waitcnt vmcnt(0)
	v_add_u32_e32 v16, v16, v14
	v_cmp_eq_u32_e32 vcc, s0, v16
	s_cbranch_vccnz .LBB0_690
	s_and_b32 s12, s5, 0xff
	s_cmp_eq_u32 s12, 0
	s_mov_b64 s[92:93], -1
	s_sleep 0
	s_cbranch_scc1 .LBB0_695
	s_and_b64 vcc, exec, s[92:93]
	s_cbranch_vccz .LBB0_690

; __device__ __forceinline__ unsigned xb_ld(unsigned* p)              { return __hip_atomic_load(p, __ATOMIC_RELAXED, __HIP_MEMORY_SCOPE_AGENT); }
; __device__ __forceinline__ void xcd_barrier_complete(unsigned* bar, unsigned x, unsigned& nloc, unsigned& nx) {
;     ...
;     for (;;) {
;         sum = 0u; cnt = 0u; mine = 0u;
; #pragma unroll
;         for (unsigned j = 0; j < 16; ++j) { const unsigned c = xb_ld(&bar[XB_XCNT(j)]); sum += c; cnt += (c > 0u) ? 1u : 0u; mine = (j == x) ? c : mine; }
;         if (sum == G) break;
;         __builtin_amdgcn_s_sleep(1);
;         if ((++sp & 255u) == 0u) { if (xb_ld(&bar[XB_TMO])) break; if (sp > XB_SPIN_CAP) { atomicAdd(&bar[XB_TMO], 1u); break; } }
;     }
.LBB0_774:
	global_load_dword v15, v129, s[16:17] sc1
	s_waitcnt lgkmcnt(0)
	global_load_dword v0, v129, s[22:23] sc1
	global_load_dword v1, v129, s[26:27] sc1
	global_load_dword v2, v129, s[38:39] sc1
	global_load_dword v3, v129, s[40:41] sc1
	global_load_dword v4, v129, s[54:55] sc1
	global_load_dword v5, v129, s[56:57] sc1
	global_load_dword v6, v129, s[58:59] sc1
	global_load_dword v7, v129, s[62:63] sc1
	global_load_dword v8, v129, s[72:73] sc1
	global_load_dword v9, v129, s[74:75] sc1
	global_load_dword v10, v129, s[76:77] sc1
	global_load_dword v11, v129, s[78:79] sc1
	global_load_dword v12, v129, s[80:81] sc1
	global_load_dword v13, v129, s[82:83] sc1
	global_load_dword v14, v129, s[84:85] sc1
	s_mov_b64 s[86:87], -1
	s_mov_b64 s[88:89], -1
	s_waitcnt vmcnt(14)
	v_add_u32_e32 v16, v0, v15
	s_waitcnt vmcnt(13)
	v_add_u32_e32 v16, v16, v1
	s_waitcnt vmcnt(12)
	v_add_u32_e32 v16, v16, v2
	s_waitcnt vmcnt(11)
	v_add_u32_e32 v16, v16, v3
	s_waitcnt vmcnt(10)
	v_add_u32_e32 v16, v16, v4
	s_waitcnt vmcnt(9)
	v_add_u32_e32 v16, v16, v5
	s_waitcnt vmcnt(8)
	v_add_u32_e32 v16, v16, v6
	s_waitcnt vmcnt(7)
	v_add_u32_e32 v16, v16, v7
	s_waitcnt vmcnt(6)
	v_add_u32_e32 v16, v16, v8
	s_waitcnt vmcnt(5)
	v_add_u32_e32 v16, v16, v9
	s_waitcnt vmcnt(4)
	v_add_u32_e32 v16, v16, v10
	s_waitcnt vmcnt(3)
	v_add_u32_e32 v16, v16, v11
	s_waitcnt vmcnt(2)
	v_add_u32_e32 v16, v16, v12
	s_waitcnt vmcnt(1)
	v_add_u32_e32 v16, v16, v13
	s_waitcnt vmcnt(0)
	v_add_u32_e32 v16, v16, v14
	v_cmp_eq_u32_e32 vcc, s0, v16
	s_cbranch_vccnz .LBB0_773
	s_and_b32 s12, s5, 0xff
	s_cmp_eq_u32 s12, 0
	s_mov_b64 s[90:91], -1
	s_sleep 0
	s_cbranch_scc1 .LBB0_778
	s_and_b64 vcc, exec, s[90:91]
	s_cbranch_vccz .LBB0_773

; __device__ __forceinline__ unsigned xb_ld(unsigned* p)              { return __hip_atomic_load(p, __ATOMIC_RELAXED, __HIP_MEMORY_SCOPE_AGENT); }
; __device__ __forceinline__ void xcd_barrier_complete(unsigned* bar, unsigned x, unsigned& nloc, unsigned& nx) {
;     ...
;     for (;;) {
;         sum = 0u; cnt = 0u; mine = 0u;
; #pragma unroll
;         for (unsigned j = 0; j < 16; ++j) { const unsigned c = xb_ld(&bar[XB_XCNT(j)]); sum += c; cnt += (c > 0u) ? 1u : 0u; mine = (j == x) ? c : mine; }
;         if (sum == G) break;
;         __builtin_amdgcn_s_sleep(1);
;         if ((++sp & 255u) == 0u) { if (xb_ld(&bar[XB_TMO])) break; if (sp > XB_SPIN_CAP) { atomicAdd(&bar[XB_TMO], 1u); break; } }
;     }
.LBB0_860:
	global_load_dword v15, v129, s[16:17] sc1
	s_waitcnt lgkmcnt(0)
	global_load_dword v0, v129, s[22:23] sc1
	global_load_dword v1, v129, s[26:27] sc1
	global_load_dword v2, v129, s[38:39] sc1
	global_load_dword v3, v129, s[40:41] sc1
	global_load_dword v4, v129, s[54:55] sc1
	global_load_dword v5, v129, s[56:57] sc1
	global_load_dword v6, v129, s[58:59] sc1
	global_load_dword v7, v129, s[62:63] sc1
	global_load_dword v8, v129, s[70:71] sc1
	global_load_dword v9, v129, s[72:73] sc1
	global_load_dword v10, v129, s[74:75] sc1
	global_load_dword v11, v129, s[76:77] sc1
	global_load_dword v12, v129, s[78:79] sc1
	global_load_dword v13, v129, s[80:81] sc1
	global_load_dword v14, v129, s[82:83] sc1
	s_mov_b64 s[84:85], -1
	s_mov_b64 s[86:87], -1
	s_waitcnt vmcnt(14)
	v_add_u32_e32 v16, v0, v15
	s_waitcnt vmcnt(13)
	v_add_u32_e32 v16, v16, v1
	s_waitcnt vmcnt(12)
	v_add_u32_e32 v16, v16, v2
	s_waitcnt vmcnt(11)
	v_add_u32_e32 v16, v16, v3
	s_waitcnt vmcnt(10)
	v_add_u32_e32 v16, v16, v4
	s_waitcnt vmcnt(9)
	v_add_u32_e32 v16, v16, v5
	s_waitcnt vmcnt(8)
	v_add_u32_e32 v16, v16, v6
	s_waitcnt vmcnt(7)
	v_add_u32_e32 v16, v16, v7
	s_waitcnt vmcnt(6)
	v_add_u32_e32 v16, v16, v8
	s_waitcnt vmcnt(5)
	v_add_u32_e32 v16, v16, v9
	s_waitcnt vmcnt(4)
	v_add_u32_e32 v16, v16, v10
	s_waitcnt vmcnt(3)
	v_add_u32_e32 v16, v16, v11
	s_waitcnt vmcnt(2)
	v_add_u32_e32 v16, v16, v12
	s_waitcnt vmcnt(1)
	v_add_u32_e32 v16, v16, v13
	s_waitcnt vmcnt(0)
	v_add_u32_e32 v16, v16, v14
	v_cmp_eq_u32_e32 vcc, s0, v16
	s_cbranch_vccnz .LBB0_859
	s_and_b32 s12, s5, 0xff
	s_cmp_eq_u32 s12, 0
	s_mov_b64 s[88:89], -1
	s_sleep 0
	s_cbranch_scc1 .LBB0_864
	s_and_b64 vcc, exec, s[88:89]
	s_cbranch_vccz .LBB0_859

; __device__ __forceinline__ unsigned xb_ld(unsigned* p)              { return __hip_atomic_load(p, __ATOMIC_RELAXED, __HIP_MEMORY_SCOPE_AGENT); }
; __device__ __forceinline__ void xcd_barrier_complete(unsigned* bar, unsigned x, unsigned& nloc, unsigned& nx) {
;     ...
;     for (;;) {
;         sum = 0u; cnt = 0u; mine = 0u;
; #pragma unroll
;         for (unsigned j = 0; j < 16; ++j) { const unsigned c = xb_ld(&bar[XB_XCNT(j)]); sum += c; cnt += (c > 0u) ? 1u : 0u; mine = (j == x) ? c : mine; }
;         if (sum == G) break;
;         __builtin_amdgcn_s_sleep(1);
;         if ((++sp & 255u) == 0u) { if (xb_ld(&bar[XB_TMO])) break; if (sp > XB_SPIN_CAP) { atomicAdd(&bar[XB_TMO], 1u); break; } }
;     }
.LBB0_916:
	global_load_dword v15, v16, s[12:13] sc1
	s_waitcnt lgkmcnt(0)
	global_load_dword v0, v16, s[14:15] sc1
	global_load_dword v1, v16, s[16:17] sc1
	global_load_dword v2, v16, s[18:19] sc1
	global_load_dword v3, v16, s[20:21] sc1
	global_load_dword v4, v16, s[22:23] sc1
	global_load_dword v5, v16, s[24:25] sc1
	global_load_dword v6, v16, s[26:27] sc1
	global_load_dword v7, v16, s[38:39] sc1
	global_load_dword v8, v16, s[40:41] sc1
	global_load_dword v9, v16, s[42:43] sc1
	global_load_dword v10, v16, s[44:45] sc1
	global_load_dword v11, v16, s[46:47] sc1
	global_load_dword v12, v16, s[48:49] sc1
	global_load_dword v13, v16, s[50:51] sc1
	global_load_dword v14, v16, s[52:53] sc1
	v_readlane_b32 s30, v254, 10
	s_mov_b64 s[54:55], -1
	s_mov_b64 s[56:57], -1
	s_waitcnt vmcnt(14)
	v_add_u32_e32 v17, v0, v15
	s_waitcnt vmcnt(13)
	v_add_u32_e32 v17, v17, v1
	s_waitcnt vmcnt(12)
	v_add_u32_e32 v17, v17, v2
	s_waitcnt vmcnt(11)
	v_add_u32_e32 v17, v17, v3
	s_waitcnt vmcnt(10)
	v_add_u32_e32 v17, v17, v4
	s_waitcnt vmcnt(9)
	v_add_u32_e32 v17, v17, v5
	s_waitcnt vmcnt(8)
	v_add_u32_e32 v17, v17, v6
	s_waitcnt vmcnt(7)
	v_add_u32_e32 v17, v17, v7
	s_waitcnt vmcnt(6)
	v_add_u32_e32 v17, v17, v8
	s_waitcnt vmcnt(5)
	v_add_u32_e32 v17, v17, v9
	s_waitcnt vmcnt(4)
	v_add_u32_e32 v17, v17, v10
	s_waitcnt vmcnt(3)
	v_add_u32_e32 v17, v17, v11
	s_waitcnt vmcnt(2)
	v_add_u32_e32 v17, v17, v12
	s_waitcnt vmcnt(1)
	v_add_u32_e32 v17, v17, v13
	s_waitcnt vmcnt(0)
	v_add_u32_e32 v17, v17, v14
	v_cmp_eq_u32_e32 vcc, s30, v17
	s_cbranch_vccnz .LBB0_915
	s_and_b32 s30, s5, 0xff
	s_cmp_eq_u32 s30, 0
	s_mov_b64 s[58:59], -1
	s_sleep 0
	s_cbranch_scc1 .LBB0_920
	s_and_b64 vcc, exec, s[58:59]
	s_cbranch_vccz .LBB0_915

; __device__ __forceinline__ unsigned xb_ld(unsigned* p)              { return __hip_atomic_load(p, __ATOMIC_RELAXED, __HIP_MEMORY_SCOPE_AGENT); }
; __device__ __forceinline__ unsigned xb_add(unsigned* p, unsigned v) { return __hip_atomic_fetch_add(p, v, __ATOMIC_RELAXED, __HIP_MEMORY_SCOPE_AGENT); }
; #define XB_SPIN(cond, bar) do { unsigned _sp = 0; while (cond) { __builtin_amdgcn_s_sleep(1); \
;     if ((++_sp & 255u) == 0u) { if (xb_ld(&(bar)[XB_TMO])) break; if (_sp > XB_SPIN_CAP) { atomicAdd(&(bar)[XB_TMO], 1u); break; } } } } while (0)
; __device__ __forceinline__ void xcd_barrier(const XcdBarrier& b) {
;     ...
;             else XB_SPIN(xb_ld(&bar[XB_TOPGEN]) == tg, bar);
;             __builtin_amdgcn_fence(__ATOMIC_ACQUIRE, "agent");
;             xb_add(&bar[XB_XGEN(b.x)], 1u);
;             asm volatile("s_waitcnt vmcnt(0)" ::: "memory");
;         } else {
;             XB_SPIN(xb_ld(&bar[XB_XGEN(b.x)]) == gen, bar);
.LBB0_934:
	s_and_b32 s5, s4, 0xff
	s_mov_b64 s[24:25], -1
	s_cmp_lg_u32 s5, 0
	s_mov_b64 s[38:39], -1
	s_sleep 0
	s_cbranch_scc0 .LBB0_937
	s_and_b64 vcc, exec, s[38:39]
	s_cbranch_vccz .LBB0_933

; __device__ __forceinline__ unsigned xb_ld(unsigned* p)              { return __hip_atomic_load(p, __ATOMIC_RELAXED, __HIP_MEMORY_SCOPE_AGENT); }
; #define XB_SPIN(cond, bar) do { unsigned _sp = 0; while (cond) { __builtin_amdgcn_s_sleep(1); \
;     if ((++_sp & 255u) == 0u) { if (xb_ld(&(bar)[XB_TMO])) break; if (_sp > XB_SPIN_CAP) { atomicAdd(&(bar)[XB_TMO], 1u); break; } } } } while (0)
; __device__ __forceinline__ void xcd_barrier(const XcdBarrier& b) {
;     ...
;             XB_SPIN(xb_ld(&bar[XB_XGEN(b.x)]) == gen, bar);
.LBB0_951:
	s_and_b32 s5, s4, 0xff
	s_cmp_lg_u32 s5, 0
	s_mov_b64 s[24:25], -1
	s_sleep 0
	s_cbranch_scc0 .LBB0_954
	s_mov_b64 s[26:27], -1
	s_and_b64 vcc, exec, s[24:25]
	s_cbranch_vccz .LBB0_950

; __device__ __forceinline__ unsigned xb_ld(unsigned* p)              { return __hip_atomic_load(p, __ATOMIC_RELAXED, __HIP_MEMORY_SCOPE_AGENT); }
; __device__ __forceinline__ void xcd_barrier_complete(unsigned* bar, unsigned x, unsigned& nloc, unsigned& nx) {
;     ...
;     for (;;) {
;         sum = 0u; cnt = 0u; mine = 0u;
; #pragma unroll
;         for (unsigned j = 0; j < 16; ++j) { const unsigned c = xb_ld(&bar[XB_XCNT(j)]); sum += c; cnt += (c > 0u) ? 1u : 0u; mine = (j == x) ? c : mine; }
;         if (sum == G) break;
;         __builtin_amdgcn_s_sleep(1);
;         if ((++sp & 255u) == 0u) { if (xb_ld(&bar[XB_TMO])) break; if (sp > XB_SPIN_CAP) { atomicAdd(&bar[XB_TMO], 1u); break; } }
;     }
.LBB0_1028:
	global_load_dword v15, v16, s[14:15] sc1
	s_waitcnt lgkmcnt(0)
	global_load_dword v0, v16, s[18:19] sc1
	global_load_dword v1, v16, s[20:21] sc1
	global_load_dword v2, v16, s[22:23] sc1
	global_load_dword v3, v16, s[24:25] sc1
	global_load_dword v4, v16, s[26:27] sc1
	global_load_dword v5, v16, s[38:39] sc1
	global_load_dword v6, v16, s[40:41] sc1
	global_load_dword v7, v16, s[42:43] sc1
	global_load_dword v8, v16, s[44:45] sc1
	global_load_dword v9, v16, s[46:47] sc1
	global_load_dword v10, v16, s[48:49] sc1
	global_load_dword v11, v16, s[50:51] sc1
	global_load_dword v12, v16, s[52:53] sc1
	global_load_dword v13, v16, s[54:55] sc1
	global_load_dword v14, v16, s[56:57] sc1
	v_readlane_b32 s30, v254, 10
	s_mov_b64 s[58:59], -1
	s_mov_b64 s[60:61], -1
	s_waitcnt vmcnt(14)
	v_add_u32_e32 v17, v0, v15
	s_waitcnt vmcnt(13)
	v_add_u32_e32 v17, v17, v1
	s_waitcnt vmcnt(12)
	v_add_u32_e32 v17, v17, v2
	s_waitcnt vmcnt(11)
	v_add_u32_e32 v17, v17, v3
	s_waitcnt vmcnt(10)
	v_add_u32_e32 v17, v17, v4
	s_waitcnt vmcnt(9)
	v_add_u32_e32 v17, v17, v5
	s_waitcnt vmcnt(8)
	v_add_u32_e32 v17, v17, v6
	s_waitcnt vmcnt(7)
	v_add_u32_e32 v17, v17, v7
	s_waitcnt vmcnt(6)
	v_add_u32_e32 v17, v17, v8
	s_waitcnt vmcnt(5)
	v_add_u32_e32 v17, v17, v9
	s_waitcnt vmcnt(4)
	v_add_u32_e32 v17, v17, v10
	s_waitcnt vmcnt(3)
	v_add_u32_e32 v17, v17, v11
	s_waitcnt vmcnt(2)
	v_add_u32_e32 v17, v17, v12
	s_waitcnt vmcnt(1)
	v_add_u32_e32 v17, v17, v13
	s_waitcnt vmcnt(0)
	v_add_u32_e32 v17, v17, v14
	v_cmp_eq_u32_e32 vcc, s30, v17
	s_cbranch_vccnz .LBB0_1027
	s_and_b32 s30, s5, 0xff
	s_cmp_eq_u32 s30, 0
	s_mov_b64 s[62:63], -1
	s_sleep 0
	s_cbranch_scc1 .LBB0_1032
	s_and_b64 vcc, exec, s[62:63]
	s_cbranch_vccz .LBB0_1027

; __device__ __forceinline__ unsigned xb_ld(unsigned* p)              { return __hip_atomic_load(p, __ATOMIC_RELAXED, __HIP_MEMORY_SCOPE_AGENT); }
; #define XB_SPIN(cond, bar) do { unsigned _sp = 0; while (cond) { __builtin_amdgcn_s_sleep(1); \
;     if ((++_sp & 255u) == 0u) { if (xb_ld(&(bar)[XB_TMO])) break; if (_sp > XB_SPIN_CAP) { atomicAdd(&(bar)[XB_TMO], 1u); break; } } } } while (0)
; __device__ __forceinline__ void xcd_barrier(const XcdBarrier& b) {
;     ...
;             else XB_SPIN(xb_ld(&bar[XB_TOPGEN]) == tg, bar);
.LBB0_1046:
	s_and_b32 s5, s4, 0xff
	s_mov_b64 s[38:39], -1
	s_cmp_lg_u32 s5, 0
	s_mov_b64 s[42:43], -1
	s_sleep 0
	s_cbranch_scc0 .LBB0_1049
	s_and_b64 vcc, exec, s[42:43]
	s_cbranch_vccz .LBB0_1045

; __device__ __forceinline__ unsigned xb_ld(unsigned* p)              { return __hip_atomic_load(p, __ATOMIC_RELAXED, __HIP_MEMORY_SCOPE_AGENT); }
; #define XB_SPIN(cond, bar) do { unsigned _sp = 0; while (cond) { __builtin_amdgcn_s_sleep(1); \
;     if ((++_sp & 255u) == 0u) { if (xb_ld(&(bar)[XB_TMO])) break; if (_sp > XB_SPIN_CAP) { atomicAdd(&(bar)[XB_TMO], 1u); break; } } } } while (0)
; __device__ __forceinline__ void xcd_barrier(const XcdBarrier& b) {
;     ...
;             XB_SPIN(xb_ld(&bar[XB_XGEN(b.x)]) == gen, bar);
.LBB0_1063:
	s_and_b32 s5, s4, 0xff
	s_cmp_lg_u32 s5, 0
	s_mov_b64 s[38:39], -1
	s_sleep 0
	s_cbranch_scc0 .LBB0_1066
	s_mov_b64 s[40:41], -1
	s_and_b64 vcc, exec, s[38:39]
	s_cbranch_vccz .LBB0_1062

; __device__ __forceinline__ unsigned xb_ld(unsigned* p)              { return __hip_atomic_load(p, __ATOMIC_RELAXED, __HIP_MEMORY_SCOPE_AGENT); }
; __device__ __forceinline__ void xcd_barrier_complete(unsigned* bar, unsigned x, unsigned& nloc, unsigned& nx) {
;     ...
;     for (;;) {
;         sum = 0u; cnt = 0u; mine = 0u;
; #pragma unroll
;         for (unsigned j = 0; j < 16; ++j) { const unsigned c = xb_ld(&bar[XB_XCNT(j)]); sum += c; cnt += (c > 0u) ? 1u : 0u; mine = (j == x) ? c : mine; }
;         if (sum == G) break;
;         __builtin_amdgcn_s_sleep(1);
;         if ((++sp & 255u) == 0u) { if (xb_ld(&bar[XB_TMO])) break; if (sp > XB_SPIN_CAP) { atomicAdd(&bar[XB_TMO], 1u); break; } }
;     }
.LBB0_1131:
	global_load_dword v15, v16, s[14:15] sc1
	s_waitcnt lgkmcnt(0)
	global_load_dword v0, v16, s[16:17] sc1
	global_load_dword v1, v16, s[18:19] sc1
	global_load_dword v2, v16, s[20:21] sc1
	global_load_dword v3, v16, s[22:23] sc1
	global_load_dword v4, v16, s[24:25] sc1
	global_load_dword v5, v16, s[26:27] sc1
	global_load_dword v6, v16, s[38:39] sc1
	global_load_dword v7, v16, s[40:41] sc1
	global_load_dword v8, v16, s[42:43] sc1
	global_load_dword v9, v16, s[44:45] sc1
	global_load_dword v10, v16, s[46:47] sc1
	global_load_dword v11, v16, s[48:49] sc1
	global_load_dword v12, v16, s[50:51] sc1
	global_load_dword v13, v16, s[52:53] sc1
	global_load_dword v14, v16, s[54:55] sc1
	v_readlane_b32 s30, v254, 10
	s_mov_b64 s[56:57], -1
	s_mov_b64 s[58:59], -1
	s_waitcnt vmcnt(14)
	v_add_u32_e32 v17, v0, v15
	s_waitcnt vmcnt(13)
	v_add_u32_e32 v17, v17, v1
	s_waitcnt vmcnt(12)
	v_add_u32_e32 v17, v17, v2
	s_waitcnt vmcnt(11)
	v_add_u32_e32 v17, v17, v3
	s_waitcnt vmcnt(10)
	v_add_u32_e32 v17, v17, v4
	s_waitcnt vmcnt(9)
	v_add_u32_e32 v17, v17, v5
	s_waitcnt vmcnt(8)
	v_add_u32_e32 v17, v17, v6
	s_waitcnt vmcnt(7)
	v_add_u32_e32 v17, v17, v7
	s_waitcnt vmcnt(6)
	v_add_u32_e32 v17, v17, v8
	s_waitcnt vmcnt(5)
	v_add_u32_e32 v17, v17, v9
	s_waitcnt vmcnt(4)
	v_add_u32_e32 v17, v17, v10
	s_waitcnt vmcnt(3)
	v_add_u32_e32 v17, v17, v11
	s_waitcnt vmcnt(2)
	v_add_u32_e32 v17, v17, v12
	s_waitcnt vmcnt(1)
	v_add_u32_e32 v17, v17, v13
	s_waitcnt vmcnt(0)
	v_add_u32_e32 v17, v17, v14
	v_cmp_eq_u32_e32 vcc, s30, v17
	s_cbranch_vccnz .LBB0_1130
	s_and_b32 s30, s5, 0xff
	s_cmp_eq_u32 s30, 0
	s_mov_b64 s[60:61], -1
	s_sleep 0
	s_cbranch_scc1 .LBB0_1135
	s_and_b64 vcc, exec, s[60:61]
	s_cbranch_vccz .LBB0_1130

; __device__ __forceinline__ unsigned xb_ld(unsigned* p)              { return __hip_atomic_load(p, __ATOMIC_RELAXED, __HIP_MEMORY_SCOPE_AGENT); }
; #define XB_SPIN(cond, bar) do { unsigned _sp = 0; while (cond) { __builtin_amdgcn_s_sleep(1); \
;     if ((++_sp & 255u) == 0u) { if (xb_ld(&(bar)[XB_TMO])) break; if (_sp > XB_SPIN_CAP) { atomicAdd(&(bar)[XB_TMO], 1u); break; } } } } while (0)
; __device__ __forceinline__ void xcd_barrier(const XcdBarrier& b) {
;     ...
;             else XB_SPIN(xb_ld(&bar[XB_TOPGEN]) == tg, bar);
.LBB0_1149:
	s_and_b32 s5, s4, 0xff
	s_mov_b64 s[26:27], -1
	s_cmp_lg_u32 s5, 0
	s_mov_b64 s[40:41], -1
	s_sleep 0
	s_cbranch_scc0 .LBB0_1152
	s_and_b64 vcc, exec, s[40:41]
	s_cbranch_vccz .LBB0_1148

; __device__ __forceinline__ unsigned xb_ld(unsigned* p)              { return __hip_atomic_load(p, __ATOMIC_RELAXED, __HIP_MEMORY_SCOPE_AGENT); }
; #define XB_SPIN(cond, bar) do { unsigned _sp = 0; while (cond) { __builtin_amdgcn_s_sleep(1); \
;     if ((++_sp & 255u) == 0u) { if (xb_ld(&(bar)[XB_TMO])) break; if (_sp > XB_SPIN_CAP) { atomicAdd(&(bar)[XB_TMO], 1u); break; } } } } while (0)
; __device__ __forceinline__ void xcd_barrier(const XcdBarrier& b) {
;     ...
;             XB_SPIN(xb_ld(&bar[XB_XGEN(b.x)]) == gen, bar);
.LBB0_1166:
	s_and_b32 s5, s4, 0xff
	s_cmp_lg_u32 s5, 0
	s_mov_b64 s[26:27], -1
	s_sleep 0
	s_cbranch_scc0 .LBB0_1169
	s_mov_b64 s[38:39], -1
	s_and_b64 vcc, exec, s[26:27]
	s_cbranch_vccz .LBB0_1165

; __device__ __forceinline__ unsigned xb_ld(unsigned* p)              { return __hip_atomic_load(p, __ATOMIC_RELAXED, __HIP_MEMORY_SCOPE_AGENT); }
; __device__ __forceinline__ void xcd_barrier_complete(unsigned* bar, unsigned x, unsigned& nloc, unsigned& nx) {
;     ...
;     for (;;) {
;         sum = 0u; cnt = 0u; mine = 0u;
; #pragma unroll
;         for (unsigned j = 0; j < 16; ++j) { const unsigned c = xb_ld(&bar[XB_XCNT(j)]); sum += c; cnt += (c > 0u) ? 1u : 0u; mine = (j == x) ? c : mine; }
;         if (sum == G) break;
;         __builtin_amdgcn_s_sleep(1);
;         if ((++sp & 255u) == 0u) { if (xb_ld(&bar[XB_TMO])) break; if (sp > XB_SPIN_CAP) { atomicAdd(&bar[XB_TMO], 1u); break; } }
;     }
.LBB0_1576:
	global_load_dword v15, v16, s[8:9] sc1
	s_waitcnt lgkmcnt(0)
	global_load_dword v0, v16, s[10:11] sc1
	global_load_dword v1, v16, s[12:13] sc1
	global_load_dword v2, v16, s[14:15] sc1
	global_load_dword v3, v16, s[16:17] sc1
	global_load_dword v4, v16, s[18:19] sc1
	global_load_dword v5, v16, s[20:21] sc1
	global_load_dword v6, v16, s[22:23] sc1
	global_load_dword v7, v16, s[24:25] sc1
	global_load_dword v8, v16, s[26:27] sc1
	global_load_dword v9, v16, s[28:29] sc1
	global_load_dword v10, v16, s[38:39] sc1
	global_load_dword v11, v16, s[40:41] sc1
	global_load_dword v12, v16, s[42:43] sc1
	global_load_dword v13, v16, s[44:45] sc1
	global_load_dword v14, v16, s[46:47] sc1
	v_readlane_b32 s30, v254, 10
	s_mov_b64 s[48:49], -1
	s_mov_b64 s[50:51], -1
	s_waitcnt vmcnt(14)
	v_add_u32_e32 v17, v0, v15
	s_waitcnt vmcnt(13)
	v_add_u32_e32 v17, v17, v1
	s_waitcnt vmcnt(12)
	v_add_u32_e32 v17, v17, v2
	s_waitcnt vmcnt(11)
	v_add_u32_e32 v17, v17, v3
	s_waitcnt vmcnt(10)
	v_add_u32_e32 v17, v17, v4
	s_waitcnt vmcnt(9)
	v_add_u32_e32 v17, v17, v5
	s_waitcnt vmcnt(8)
	v_add_u32_e32 v17, v17, v6
	s_waitcnt vmcnt(7)
	v_add_u32_e32 v17, v17, v7
	s_waitcnt vmcnt(6)
	v_add_u32_e32 v17, v17, v8
	s_waitcnt vmcnt(5)
	v_add_u32_e32 v17, v17, v9
	s_waitcnt vmcnt(4)
	v_add_u32_e32 v17, v17, v10
	s_waitcnt vmcnt(3)
	v_add_u32_e32 v17, v17, v11
	s_waitcnt vmcnt(2)
	v_add_u32_e32 v17, v17, v12
	s_waitcnt vmcnt(1)
	v_add_u32_e32 v17, v17, v13
	s_waitcnt vmcnt(0)
	v_add_u32_e32 v17, v17, v14
	v_cmp_eq_u32_e32 vcc, s30, v17
	s_cbranch_vccnz .LBB0_1575
	s_and_b32 s30, s33, 0xff
	s_cmp_eq_u32 s30, 0
	s_mov_b64 s[52:53], -1
	s_sleep 0
	s_cbranch_scc1 .LBB0_1580
	s_and_b64 vcc, exec, s[52:53]
	s_cbranch_vccz .LBB0_1575

; __device__ __forceinline__ unsigned xb_ld(unsigned* p)              { return __hip_atomic_load(p, __ATOMIC_RELAXED, __HIP_MEMORY_SCOPE_AGENT); }
; #define XB_SPIN(cond, bar) do { unsigned _sp = 0; while (cond) { __builtin_amdgcn_s_sleep(1); \
;     if ((++_sp & 255u) == 0u) { if (xb_ld(&(bar)[XB_TMO])) break; if (_sp > XB_SPIN_CAP) { atomicAdd(&(bar)[XB_TMO], 1u); break; } } } } while (0)
; __device__ __forceinline__ void xcd_barrier(const XcdBarrier& b) {
;     ...
;             else XB_SPIN(xb_ld(&bar[XB_TOPGEN]) == tg, bar);
.LBB0_1594:
	s_and_b32 s22, s26, 0xff
	s_mov_b64 s[20:21], -1
	s_cmp_lg_u32 s22, 0
	s_mov_b64 s[24:25], -1
	s_sleep 0
	s_cbranch_scc0 .LBB0_1597
	s_and_b64 vcc, exec, s[24:25]
	s_cbranch_vccz .LBB0_1593

; __device__ __forceinline__ unsigned xb_ld(unsigned* p)              { return __hip_atomic_load(p, __ATOMIC_RELAXED, __HIP_MEMORY_SCOPE_AGENT); }
; #define XB_SPIN(cond, bar) do { unsigned _sp = 0; while (cond) { __builtin_amdgcn_s_sleep(1); \
;     if ((++_sp & 255u) == 0u) { if (xb_ld(&(bar)[XB_TMO])) break; if (_sp > XB_SPIN_CAP) { atomicAdd(&(bar)[XB_TMO], 1u); break; } } } } while (0)
; __device__ __forceinline__ void xcd_barrier(const XcdBarrier& b) {
;     ...
;             XB_SPIN(xb_ld(&bar[XB_XGEN(b.x)]) == gen, bar);
.LBB0_1611:
	s_and_b32 s18, s24, 0xff
	s_cmp_lg_u32 s18, 0
	s_mov_b64 s[20:21], -1
	s_sleep 0
	s_cbranch_scc0 .LBB0_1614
	s_mov_b64 s[22:23], -1
	s_and_b64 vcc, exec, s[20:21]
	s_cbranch_vccz .LBB0_1610
